# v41 + sample-chain waits before the P4/P5/P6 thin units: counter requested before the store drain, poll loop skipped when it already reads complete (acquire kept)
# speedup vs baseline: 1.0223x; 1.0040x over previous
.LBB0_633:
	s_mov_b64 s[100:101], exec
	v_readlane_b32 s98, v251, 41
	v_readlane_b32 s99, v251, 42
	s_and_b64 s[98:99], s[100:101], s[98:99]
	s_mov_b64 exec, s[98:99]
	s_cbranch_execz .Lmy_pf4_skip
	v_readlane_b32 s98, v251, 20
	v_readlane_b32 s99, v251, 21
	s_add_u32 s98, s98, 0x28000
	s_addc_u32 s99, s99, 0
	v_mov_b32_e32 v252, 0
	global_load_dword v253, v252, s[98:99] sc1
.Lmy_pf4_skip:
	s_mov_b64 exec, s[100:101]
	s_waitcnt vmcnt(0)
	s_waitcnt vmcnt(0)
	s_barrier
	s_mov_b64 s[4:5], exec
	v_readlane_b32 s16, v251, 41
	v_readlane_b32 s17, v251, 42
	s_and_b64 s[16:17], s[4:5], s[16:17]
	s_mov_b64 exec, s[16:17]
	s_cbranch_execz .LBB0_636
	s_mov_b64 s[16:17], exec
	v_mbcnt_lo_u32_b32 v2, s16, 0
	v_mbcnt_hi_u32_b32 v2, s17, v2
	v_cmp_eq_u32_e32 vcc, 0, v2
	s_and_b64 s[18:19], exec, vcc
	s_mov_b64 exec, s[18:19]
	s_cbranch_execz .LBB0_636
	s_bcnt1_i32_b64 s1, s[16:17]
	v_mov_b32_e32 v2, 0
	v_mov_b32_e32 v3, s1
	global_atomic_add v2, v3, s[28:29]
.LBB0_636:
	s_or_b64 exec, exec, s[4:5]
	s_sub_i32 s1, s70, 64
	s_cmpk_gt_u32 s1, 0x7f
	s_cbranch_scc1 .LBB0_653
	s_and_saveexec_b64 s[4:5], s[2:3]
	s_cbranch_execz .LBB0_649
	v_readfirstlane_b32 s98, v253
	s_cmpk_gt_u32 s98, 0x7f
	s_cbranch_scc1 .LBB0_648
	s_memrealtime s[2:3]
	v_mov_b32_e32 v4, 0
	v_mov_b64_e32 v[2:3], 0x1e8481
	s_branch .LBB0_641

.LBB0_707:
	s_mov_b64 s[100:101], exec
	v_readlane_b32 s98, v251, 41
	v_readlane_b32 s99, v251, 42
	s_and_b64 s[98:99], s[100:101], s[98:99]
	s_mov_b64 exec, s[98:99]
	s_cbranch_execz .Lmy_pf5_skip
	v_readlane_b32 s98, v251, 20
	v_readlane_b32 s99, v251, 21
	s_add_u32 s98, s98, 0x28100
	s_addc_u32 s99, s99, 0
	v_mov_b32_e32 v252, 0
	global_load_dword v253, v252, s[98:99] sc1
.Lmy_pf5_skip:
	s_mov_b64 exec, s[100:101]
	s_waitcnt vmcnt(0)
	s_waitcnt lgkmcnt(0)
	s_barrier
	s_mov_b64 s[4:5], exec
	v_readlane_b32 s6, v251, 41
	v_readlane_b32 s7, v251, 42
	s_and_b64 s[6:7], s[4:5], s[6:7]
	s_mov_b64 exec, s[6:7]
	s_cbranch_execz .LBB0_710
	s_mov_b64 s[6:7], exec
	v_mbcnt_lo_u32_b32 v2, s6, 0
	v_mbcnt_hi_u32_b32 v2, s7, v2
	v_cmp_eq_u32_e32 vcc, 0, v2
	s_and_b64 s[8:9], exec, vcc
	s_mov_b64 exec, s[8:9]
	s_cbranch_execz .LBB0_710
	s_bcnt1_i32_b64 s1, s[6:7]
	v_mov_b32_e32 v2, 0
	v_mov_b32_e32 v3, s1
	global_atomic_add v2, v3, s[26:27]
.LBB0_710:
	s_or_b64 exec, exec, s[4:5]
	s_add_i32 s1, s70, 0xffffff40
	s_cmp_gt_u32 s1, 0xffffff7f
	s_cbranch_scc1 .LBB0_732
	s_and_saveexec_b64 s[4:5], s[2:3]
	s_cbranch_execz .LBB0_723
	v_readfirstlane_b32 s98, v253
	s_cmpk_gt_u32 s98, 0x7f
	s_cbranch_scc1 .LBB0_722
	s_memrealtime s[2:3]
	v_mov_b32_e32 v4, 0
	v_mov_b64_e32 v[2:3], 0x1e8481
	s_branch .LBB0_715

.LBB0_747:
	s_or_b64 exec, exec, s[8:9]
	s_cmpk_gt_i32 s70, 0xff
	v_readfirstlane_b32 s36, v0
	s_waitcnt lgkmcnt(0)
	s_barrier
	v_mov_b32_e32 v253, 0
	s_cbranch_scc1 .LBB0_767
	s_cmp_gt_i32 s75, -1
	s_cbranch_scc0 .LBB0_750
	s_lshl_b32 s4, s75, 5
	s_cbranch_execz .LBB0_751
	s_branch .LBB0_752

.LBB0_762:
	ds_read_b128 v[130:133], v212
	ds_read_b128 v[134:137], v212 offset:1024
	ds_read_b128 v[138:141], v212 offset:2048
	ds_read_b128 v[142:145], v212 offset:3072
	ds_read_b128 v[146:149], v213
	ds_read_b128 v[150:153], v213 offset:1024
	ds_read_b128 v[154:157], v213 offset:2048
	ds_read_b128 v[158:161], v213 offset:3072
	s_add_u32 s30, s28, 0xfffc0080
	s_addc_u32 s31, s29, -1
	s_cmp_eq_u32 s49, 12
	s_cselect_b32 s35, s9, s31
	s_cselect_b32 s34, s33, s30
	s_cselect_b32 s31, s7, s48
	s_cselect_b32 s30, s46, s47
	v_lshl_add_u64 v[194:195], s[28:29], 0, v[170:171]
	s_add_i32 m0, s25, 0xc000
	ds_read_b128 v[178:181], v214
	ds_read_b128 v[182:185], v214 offset:1024
	ds_read_b128 v[216:219], v214 offset:2048
	ds_read_b128 v[220:223], v214 offset:3072
	ds_read_b128 v[224:227], v214 offset:4096
	ds_read_b128 v[228:231], v214 offset:5120
	ds_read_b128 v[232:235], v214 offset:6144
	ds_read_b128 v[236:239], v214 offset:7168
	global_load_lds_dwordx4 v[194:195], off
	v_lshl_add_u64 v[194:195], s[28:29], 0, v[172:173]
	s_add_i32 m0, s25, 0xe000
	s_nop 0
	global_load_lds_dwordx4 v[194:195], off
	s_waitcnt vmcnt(8)
	s_waitcnt lgkmcnt(0)
	s_barrier
	s_setprio 1
	s_waitcnt lgkmcnt(0)
	v_mfma_f32_16x16x32_bf16 v[126:129], v[130:133], v[178:181], v[126:129]
	v_mfma_f32_16x16x32_bf16 v[122:125], v[138:141], v[178:181], v[122:125]
	v_mfma_f32_16x16x32_bf16 v[110:113], v[130:133], v[216:219], v[110:113]
	v_mfma_f32_16x16x32_bf16 v[106:109], v[138:141], v[216:219], v[106:109]
	v_mfma_f32_16x16x32_bf16 v[94:97], v[130:133], v[224:227], v[94:97]
	v_mfma_f32_16x16x32_bf16 v[90:93], v[138:141], v[224:227], v[90:93]
	v_mfma_f32_16x16x32_bf16 v[78:81], v[130:133], v[232:235], v[78:81]
	v_mfma_f32_16x16x32_bf16 v[74:77], v[138:141], v[232:235], v[74:77]
	v_mfma_f32_16x16x32_bf16 v[126:129], v[134:137], v[182:185], v[126:129]
	v_mfma_f32_16x16x32_bf16 v[122:125], v[142:145], v[182:185], v[122:125]
	v_mfma_f32_16x16x32_bf16 v[110:113], v[134:137], v[220:223], v[110:113]
	v_mfma_f32_16x16x32_bf16 v[106:109], v[142:145], v[220:223], v[106:109]
	v_mfma_f32_16x16x32_bf16 v[94:97], v[134:137], v[228:231], v[94:97]
	v_mfma_f32_16x16x32_bf16 v[90:93], v[142:145], v[228:231], v[90:93]
	v_mfma_f32_16x16x32_bf16 v[78:81], v[134:137], v[236:239], v[78:81]
	v_mfma_f32_16x16x32_bf16 v[74:77], v[142:145], v[236:239], v[74:77]
	s_setprio 0
	s_setprio 1
	v_mfma_f32_16x16x32_bf16 v[118:121], v[146:149], v[178:181], v[118:121]
	v_mfma_f32_16x16x32_bf16 v[114:117], v[154:157], v[178:181], v[114:117]
	v_mfma_f32_16x16x32_bf16 v[102:105], v[146:149], v[216:219], v[102:105]
	v_mfma_f32_16x16x32_bf16 v[98:101], v[154:157], v[216:219], v[98:101]
	v_mfma_f32_16x16x32_bf16 v[86:89], v[146:149], v[224:227], v[86:89]
	v_mfma_f32_16x16x32_bf16 v[82:85], v[154:157], v[224:227], v[82:85]
	v_mfma_f32_16x16x32_bf16 v[70:73], v[146:149], v[232:235], v[70:73]
	v_mfma_f32_16x16x32_bf16 v[66:69], v[154:157], v[232:235], v[66:69]
	v_mfma_f32_16x16x32_bf16 v[118:121], v[150:153], v[182:185], v[118:121]
	v_mfma_f32_16x16x32_bf16 v[114:117], v[158:161], v[182:185], v[114:117]
	v_mfma_f32_16x16x32_bf16 v[102:105], v[150:153], v[220:223], v[102:105]
	v_mfma_f32_16x16x32_bf16 v[98:101], v[158:161], v[220:223], v[98:101]
	v_mfma_f32_16x16x32_bf16 v[86:89], v[150:153], v[228:231], v[86:89]
	v_mfma_f32_16x16x32_bf16 v[82:85], v[158:161], v[228:231], v[82:85]
	v_mfma_f32_16x16x32_bf16 v[70:73], v[150:153], v[236:239], v[70:73]
	v_mfma_f32_16x16x32_bf16 v[66:69], v[158:161], v[236:239], v[66:69]
	s_setprio 0
	s_barrier
	s_add_i32 s50, s44, s37
	v_lshl_add_u64 v[194:195], s[30:31], 0, v[164:165]
	s_mov_b32 m0, s50
	ds_read_b128 v[178:181], v214 offset:16384
	ds_read_b128 v[182:185], v214 offset:17408
	ds_read_b128 v[216:219], v214 offset:18432
	ds_read_b128 v[220:223], v214 offset:19456
	ds_read_b128 v[224:227], v214 offset:20480
	ds_read_b128 v[228:231], v214 offset:21504
	ds_read_b128 v[232:235], v214 offset:22528
	ds_read_b128 v[236:239], v214 offset:23552
	global_load_lds_dwordx4 v[194:195], off
	s_add_i32 m0, s50, 0x2000
	s_add_u32 s50, s30, 0x40000
	v_lshl_add_u64 v[240:241], s[30:31], 0, v[168:169]
	s_addc_u32 s51, s31, 0
	s_add_i32 s52, s45, s37
	global_load_lds_dwordx4 v[240:241], off
	v_lshl_add_u64 v[242:243], s[50:51], 0, v[164:165]
	s_mov_b32 m0, s52
	v_lshl_add_u64 v[244:245], s[34:35], 0, v[166:167]
	global_load_lds_dwordx4 v[242:243], off
	v_lshl_add_u64 v[242:243], s[50:51], 0, v[168:169]
	s_add_i32 m0, s52, 0x2000
	s_nop 0
	global_load_lds_dwordx4 v[242:243], off
	v_lshl_add_u64 v[242:243], s[34:35], 0, v[162:163]
	s_mov_b32 m0, s25
	s_nop 0
	global_load_lds_dwordx4 v[242:243], off
	s_mov_b32 m0, s27
	s_nop 0
	global_load_lds_dwordx4 v[244:245], off
	s_waitcnt vmcnt(8)
	s_waitcnt lgkmcnt(0)
	s_barrier
	s_setprio 1
	s_waitcnt lgkmcnt(0)
	v_mfma_f32_16x16x32_bf16 v[62:65], v[130:133], v[178:181], v[62:65]
	v_mfma_f32_16x16x32_bf16 v[58:61], v[138:141], v[178:181], v[58:61]
	v_mfma_f32_16x16x32_bf16 v[46:49], v[130:133], v[216:219], v[46:49]
	v_mfma_f32_16x16x32_bf16 v[42:45], v[138:141], v[216:219], v[42:45]
	v_mfma_f32_16x16x32_bf16 v[30:33], v[130:133], v[224:227], v[30:33]
	v_mfma_f32_16x16x32_bf16 v[26:29], v[138:141], v[224:227], v[26:29]
	v_mfma_f32_16x16x32_bf16 v[14:17], v[130:133], v[232:235], v[14:17]
	v_mfma_f32_16x16x32_bf16 v[10:13], v[138:141], v[232:235], v[10:13]
	v_mfma_f32_16x16x32_bf16 v[62:65], v[134:137], v[182:185], v[62:65]
	v_mfma_f32_16x16x32_bf16 v[58:61], v[142:145], v[182:185], v[58:61]
	v_mfma_f32_16x16x32_bf16 v[46:49], v[134:137], v[220:223], v[46:49]
	v_mfma_f32_16x16x32_bf16 v[42:45], v[142:145], v[220:223], v[42:45]
	v_mfma_f32_16x16x32_bf16 v[30:33], v[134:137], v[228:231], v[30:33]
	v_mfma_f32_16x16x32_bf16 v[26:29], v[142:145], v[228:231], v[26:29]
	v_mfma_f32_16x16x32_bf16 v[14:17], v[134:137], v[236:239], v[14:17]
	v_mfma_f32_16x16x32_bf16 v[10:13], v[142:145], v[236:239], v[10:13]
	s_setprio 0
	s_setprio 1
	v_mfma_f32_16x16x32_bf16 v[54:57], v[146:149], v[178:181], v[54:57]
	v_mfma_f32_16x16x32_bf16 v[50:53], v[154:157], v[178:181], v[50:53]
	v_mfma_f32_16x16x32_bf16 v[38:41], v[146:149], v[216:219], v[38:41]
	v_mfma_f32_16x16x32_bf16 v[34:37], v[154:157], v[216:219], v[34:37]
	v_mfma_f32_16x16x32_bf16 v[22:25], v[146:149], v[224:227], v[22:25]
	v_mfma_f32_16x16x32_bf16 v[18:21], v[154:157], v[224:227], v[18:21]
	v_mfma_f32_16x16x32_bf16 v[6:9], v[146:149], v[232:235], v[6:9]
	v_mfma_f32_16x16x32_bf16 v[2:5], v[154:157], v[232:235], v[2:5]
	v_mfma_f32_16x16x32_bf16 v[54:57], v[150:153], v[182:185], v[54:57]
	v_mfma_f32_16x16x32_bf16 v[50:53], v[158:161], v[182:185], v[50:53]
	v_mfma_f32_16x16x32_bf16 v[38:41], v[150:153], v[220:223], v[38:41]
	v_mfma_f32_16x16x32_bf16 v[34:37], v[158:161], v[220:223], v[34:37]
	v_mfma_f32_16x16x32_bf16 v[22:25], v[150:153], v[228:231], v[22:25]
	v_mfma_f32_16x16x32_bf16 v[18:21], v[158:161], v[228:231], v[18:21]
	v_mfma_f32_16x16x32_bf16 v[6:9], v[150:153], v[236:239], v[6:9]
	v_mfma_f32_16x16x32_bf16 v[2:5], v[158:161], v[236:239], v[2:5]
	s_setprio 0
	s_barrier
	s_add_i32 s50, 0, 0x18000
	s_add_i32 s51, 0, 0x1c000
	v_add_u32_e32 v142, s50, v191
	v_add_u32_e32 v158, s51, v191
	ds_read_b128 v[130:133], v142
	ds_read_b128 v[134:137], v142 offset:1024
	ds_read_b128 v[138:141], v142 offset:2048
	ds_read_b128 v[142:145], v142 offset:3072
	ds_read_b128 v[146:149], v158
	ds_read_b128 v[150:153], v158 offset:1024
	ds_read_b128 v[154:157], v158 offset:2048
	ds_read_b128 v[158:161], v158 offset:3072
	s_add_u32 s34, s34, 0x40000
	s_addc_u32 s35, s35, 0
	s_mov_b32 m0, s38
	v_lshl_add_u64 v[246:247], s[34:35], 0, v[162:163]
	ds_read_b128 v[178:181], v214 offset:32768
	ds_read_b128 v[182:185], v214 offset:33792
	ds_read_b128 v[216:219], v214 offset:34816
	ds_read_b128 v[220:223], v214 offset:35840
	ds_read_b128 v[224:227], v214 offset:36864
	ds_read_b128 v[228:231], v214 offset:37888
	ds_read_b128 v[232:235], v214 offset:38912
	ds_read_b128 v[236:239], v214 offset:39936
	global_load_lds_dwordx4 v[246:247], off
	v_lshl_add_u64 v[246:247], s[34:35], 0, v[166:167]
	s_mov_b32 m0, s39
	s_nop 0
	global_load_lds_dwordx4 v[246:247], off
	s_waitcnt vmcnt(8)
	s_waitcnt lgkmcnt(0)
	s_barrier
	s_setprio 1
	s_waitcnt lgkmcnt(0)
	v_mfma_f32_16x16x32_bf16 v[126:129], v[130:133], v[178:181], v[126:129]
	v_mfma_f32_16x16x32_bf16 v[122:125], v[138:141], v[178:181], v[122:125]
	v_mfma_f32_16x16x32_bf16 v[110:113], v[130:133], v[216:219], v[110:113]
	v_mfma_f32_16x16x32_bf16 v[106:109], v[138:141], v[216:219], v[106:109]
	v_mfma_f32_16x16x32_bf16 v[94:97], v[130:133], v[224:227], v[94:97]
	v_mfma_f32_16x16x32_bf16 v[90:93], v[138:141], v[224:227], v[90:93]
	v_mfma_f32_16x16x32_bf16 v[78:81], v[130:133], v[232:235], v[78:81]
	v_mfma_f32_16x16x32_bf16 v[74:77], v[138:141], v[232:235], v[74:77]
	v_mfma_f32_16x16x32_bf16 v[126:129], v[134:137], v[182:185], v[126:129]
	v_mfma_f32_16x16x32_bf16 v[122:125], v[142:145], v[182:185], v[122:125]
	v_mfma_f32_16x16x32_bf16 v[110:113], v[134:137], v[220:223], v[110:113]
	v_mfma_f32_16x16x32_bf16 v[106:109], v[142:145], v[220:223], v[106:109]
	v_mfma_f32_16x16x32_bf16 v[94:97], v[134:137], v[228:231], v[94:97]
	v_mfma_f32_16x16x32_bf16 v[90:93], v[142:145], v[228:231], v[90:93]
	v_mfma_f32_16x16x32_bf16 v[78:81], v[134:137], v[236:239], v[78:81]
	v_mfma_f32_16x16x32_bf16 v[74:77], v[142:145], v[236:239], v[74:77]
	s_setprio 0
	s_setprio 1
	v_mfma_f32_16x16x32_bf16 v[118:121], v[146:149], v[178:181], v[118:121]
	v_mfma_f32_16x16x32_bf16 v[114:117], v[154:157], v[178:181], v[114:117]
	v_mfma_f32_16x16x32_bf16 v[102:105], v[146:149], v[216:219], v[102:105]
	v_mfma_f32_16x16x32_bf16 v[98:101], v[154:157], v[216:219], v[98:101]
	v_mfma_f32_16x16x32_bf16 v[86:89], v[146:149], v[224:227], v[86:89]
	v_mfma_f32_16x16x32_bf16 v[82:85], v[154:157], v[224:227], v[82:85]
	v_mfma_f32_16x16x32_bf16 v[70:73], v[146:149], v[232:235], v[70:73]
	v_mfma_f32_16x16x32_bf16 v[66:69], v[154:157], v[232:235], v[66:69]
	v_mfma_f32_16x16x32_bf16 v[118:121], v[150:153], v[182:185], v[118:121]
	v_mfma_f32_16x16x32_bf16 v[114:117], v[158:161], v[182:185], v[114:117]
	v_mfma_f32_16x16x32_bf16 v[102:105], v[150:153], v[220:223], v[102:105]
	v_mfma_f32_16x16x32_bf16 v[98:101], v[158:161], v[220:223], v[98:101]
	v_mfma_f32_16x16x32_bf16 v[86:89], v[150:153], v[228:231], v[86:89]
	v_mfma_f32_16x16x32_bf16 v[82:85], v[158:161], v[228:231], v[82:85]
	v_mfma_f32_16x16x32_bf16 v[70:73], v[150:153], v[236:239], v[70:73]
	v_mfma_f32_16x16x32_bf16 v[66:69], v[158:161], v[236:239], v[66:69]
	s_setprio 0
	s_barrier
	s_add_i32 s34, s50, s37
	v_lshl_add_u64 v[194:195], v[194:195], 0, s[0:1]
	s_mov_b32 m0, s34
	ds_read_b128 v[178:181], v214 offset:49152
	ds_read_b128 v[182:185], v214 offset:50176
	ds_read_b128 v[216:219], v214 offset:51200
	ds_read_b128 v[220:223], v214 offset:52224
	ds_read_b128 v[224:227], v214 offset:53248
	ds_read_b128 v[228:231], v214 offset:54272
	ds_read_b128 v[232:235], v214 offset:55296
	ds_read_b128 v[236:239], v214 offset:56320
	global_load_lds_dwordx4 v[194:195], off
	s_add_i32 m0, s34, 0x2000
	s_add_u32 s30, s30, 0x40080
	v_lshl_add_u64 v[194:195], v[240:241], 0, s[0:1]
	s_addc_u32 s31, s31, 0
	s_add_i32 s34, s51, s37
	global_load_lds_dwordx4 v[194:195], off
	v_lshl_add_u64 v[194:195], s[30:31], 0, v[164:165]
	s_mov_b32 m0, s34
	s_nop 0
	global_load_lds_dwordx4 v[194:195], off
	v_lshl_add_u64 v[194:195], s[30:31], 0, v[168:169]
	s_add_i32 m0, s34, 0x2000
	s_nop 0
	global_load_lds_dwordx4 v[194:195], off
	v_lshl_add_u64 v[194:195], v[242:243], 0, s[0:1]
	s_mov_b32 m0, s41
	s_nop 0
	global_load_lds_dwordx4 v[194:195], off
	v_lshl_add_u64 v[194:195], v[244:245], 0, s[0:1]
	s_mov_b32 m0, s42
	s_nop 0
	global_load_lds_dwordx4 v[194:195], off
	s_waitcnt vmcnt(8)
	s_waitcnt lgkmcnt(0)
	s_barrier
	s_setprio 1
	s_waitcnt lgkmcnt(0)
	v_mfma_f32_16x16x32_bf16 v[62:65], v[130:133], v[178:181], v[62:65]
	v_mfma_f32_16x16x32_bf16 v[58:61], v[138:141], v[178:181], v[58:61]
	v_mfma_f32_16x16x32_bf16 v[46:49], v[130:133], v[216:219], v[46:49]
	v_mfma_f32_16x16x32_bf16 v[42:45], v[138:141], v[216:219], v[42:45]
	v_mfma_f32_16x16x32_bf16 v[30:33], v[130:133], v[224:227], v[30:33]
	v_mfma_f32_16x16x32_bf16 v[26:29], v[138:141], v[224:227], v[26:29]
	v_mfma_f32_16x16x32_bf16 v[14:17], v[130:133], v[232:235], v[14:17]
	v_mfma_f32_16x16x32_bf16 v[10:13], v[138:141], v[232:235], v[10:13]
	v_mfma_f32_16x16x32_bf16 v[62:65], v[134:137], v[182:185], v[62:65]
	v_mfma_f32_16x16x32_bf16 v[58:61], v[142:145], v[182:185], v[58:61]
	v_mfma_f32_16x16x32_bf16 v[46:49], v[134:137], v[220:223], v[46:49]
	v_mfma_f32_16x16x32_bf16 v[42:45], v[142:145], v[220:223], v[42:45]
	v_mfma_f32_16x16x32_bf16 v[30:33], v[134:137], v[228:231], v[30:33]
	v_mfma_f32_16x16x32_bf16 v[26:29], v[142:145], v[228:231], v[26:29]
	v_mfma_f32_16x16x32_bf16 v[14:17], v[134:137], v[236:239], v[14:17]
	v_mfma_f32_16x16x32_bf16 v[10:13], v[142:145], v[236:239], v[10:13]
	s_setprio 0
	s_setprio 1
	v_mfma_f32_16x16x32_bf16 v[54:57], v[146:149], v[178:181], v[54:57]
	v_mfma_f32_16x16x32_bf16 v[50:53], v[154:157], v[178:181], v[50:53]
	v_mfma_f32_16x16x32_bf16 v[38:41], v[146:149], v[216:219], v[38:41]
	v_mfma_f32_16x16x32_bf16 v[34:37], v[154:157], v[216:219], v[34:37]
	v_mfma_f32_16x16x32_bf16 v[22:25], v[146:149], v[224:227], v[22:25]
	v_mfma_f32_16x16x32_bf16 v[18:21], v[154:157], v[224:227], v[18:21]
	v_mfma_f32_16x16x32_bf16 v[6:9], v[146:149], v[232:235], v[6:9]
	v_mfma_f32_16x16x32_bf16 v[2:5], v[154:157], v[232:235], v[2:5]
	v_mfma_f32_16x16x32_bf16 v[54:57], v[150:153], v[182:185], v[54:57]
	v_mfma_f32_16x16x32_bf16 v[50:53], v[158:161], v[182:185], v[50:53]
	v_mfma_f32_16x16x32_bf16 v[38:41], v[150:153], v[220:223], v[38:41]
	v_mfma_f32_16x16x32_bf16 v[34:37], v[158:161], v[220:223], v[34:37]
	v_mfma_f32_16x16x32_bf16 v[22:25], v[150:153], v[228:231], v[22:25]
	v_mfma_f32_16x16x32_bf16 v[18:21], v[158:161], v[228:231], v[18:21]
	v_mfma_f32_16x16x32_bf16 v[6:9], v[150:153], v[236:239], v[6:9]
	v_mfma_f32_16x16x32_bf16 v[2:5], v[158:161], v[236:239], v[2:5]
	s_setprio 0
	s_barrier
	s_add_i32 s49, s49, 2
	s_add_u32 s28, s28, 0x100
	s_addc_u32 s29, s29, 0
	s_add_u32 s47, s47, 0x100
	s_addc_u32 s48, s48, 0
	s_cmp_gt_u32 s49, 13
	s_cbranch_scc0 .LBB0_762
	v_lshl_or_b32 v138, s24, 8, v211
	v_lshl_add_u32 v184, s26, 8, v1
	v_ashrrev_i32_e32 v139, 31, v138
	v_lshlrev_b64 v[182:183], 1, v[138:139]
	v_ashrrev_i32_e32 v185, 31, v184
	v_lshl_add_u64 v[146:147], s[82:83], 0, v[182:183]
	v_lshlrev_b64 v[134:135], 11, v[184:185]
	v_readlane_b32 s48, v251, 6
	v_lshl_add_u64 v[150:151], v[146:147], 0, v[134:135]
	v_readlane_b32 s58, v251, 16
	v_readlane_b32 s59, v251, 17
	v_lshl_add_u64 v[148:149], s[18:19], 0, v[182:183]
	global_load_dwordx4 v[130:133], v[150:151], off nt
	v_lshlrev_b64 v[180:181], 2, v[138:139]
	s_mov_b64 s[46:47], s[58:59]
	v_lshl_add_u64 v[152:153], v[148:149], 0, v[134:135]
	v_lshl_add_u64 v[178:179], s[46:47], 0, v[180:181]
	global_load_dwordx4 v[134:137], v[152:153], off
	global_load_dwordx4 v[162:165], v[178:179], off
	global_load_dwordx4 v[166:169], v[178:179], off offset:16
	global_load_dwordx4 v[170:173], v[178:179], off offset:512
	global_load_dwordx4 v[174:177], v[178:179], off offset:528
	ds_read_b32 v215, v193
	ds_read_b32 v186, v196
	ds_read_b32 v216, v197
	ds_read_b32 v190, v198
	ds_read_b32 v218, v199
	ds_read_b32 v192, v200
	ds_read_b32 v217, v201
	ds_read_b32 v188, v202
	s_waitcnt lgkmcnt(0)
	v_mul_f32_e32 v215, 0xbfb8aa3b, v215
	v_mul_f32_e32 v126, v126, v215
	v_mul_f32_e32 v122, v122, v215
	v_mul_f32_e32 v127, v127, v215
	v_mul_f32_e32 v123, v123, v215
	v_mul_f32_e32 v124, v124, v215
	v_exp_f32_e32 v126, v126
	v_exp_f32_e32 v122, v122
	v_exp_f32_e32 v127, v127
	v_exp_f32_e32 v123, v123
	v_exp_f32_e32 v124, v124
	v_mul_f32_e32 v128, v128, v215
	v_mul_f32_e32 v129, v129, v215
	v_mul_f32_e32 v125, v125, v215
	v_exp_f32_e32 v128, v128
	v_exp_f32_e32 v129, v129
	v_exp_f32_e32 v219, v125
	v_add_f32_e32 v125, 1.0, v126
	v_add_f32_e32 v126, 1.0, v122
	v_add_f32_e32 v127, 1.0, v127
	v_add_f32_e32 v242, 1.0, v123
	v_add_f32_e32 v243, 1.0, v124
	v_rcp_f32_e32 v122, v125
	v_rcp_f32_e32 v124, v126
	v_rcp_f32_e32 v123, v127
	v_rcp_f32_e32 v125, v242
	v_add_f32_e32 v128, 1.0, v128
	v_add_f32_e32 v129, 1.0, v129
	v_rcp_f32_e32 v128, v128
	v_rcp_f32_e32 v129, v129
	v_rcp_f32_e32 v242, v243
	v_or_b32_e32 v194, 32, v184
	v_readlane_b32 s49, v251, 7
	v_readlane_b32 s50, v251, 8
	v_readlane_b32 s51, v251, 9
	v_readlane_b32 s60, v251, 18
	v_readlane_b32 s61, v251, 19
	v_or_b32_e32 v236, 16, v184
	v_ashrrev_i32_e32 v195, 31, v194
	v_readlane_b32 s62, v251, 20
	v_readlane_b32 s63, v251, 21
	s_mov_b64 s[48:49], s[60:61]
	v_ashrrev_i32_e32 v237, 31, v236
	v_lshlrev_b64 v[156:157], 11, v[194:195]
	v_lshlrev_b64 v[154:155], 11, v[236:237]
	v_lshl_add_u64 v[238:239], s[82:83], 0, v[156:157]
	v_lshl_add_u64 v[146:147], v[146:147], 0, v[154:155]
	v_lshl_add_u64 v[148:149], v[148:149], 0, v[154:155]
	v_lshl_add_u64 v[240:241], s[18:19], 0, v[156:157]
	v_lshl_add_u64 v[238:239], v[238:239], 0, v[182:183]
	global_load_dwordx4 v[220:223], v[150:151], off offset:256 nt
	global_load_dwordx4 v[224:227], v[152:153], off offset:256
	global_load_dwordx4 v[228:231], v[146:147], off nt
	global_load_dwordx4 v[154:157], v[146:147], off offset:256 nt
	global_load_dwordx4 v[232:235], v[148:149], off
	global_load_dwordx4 v[158:161], v[148:149], off offset:256
	v_lshl_add_u64 v[240:241], v[240:241], 0, v[182:183]
	global_load_dwordx4 v[150:153], v[238:239], off nt
	global_load_dwordx4 v[146:149], v[240:241], off
	v_mul_f32_e32 v118, v118, v215
	v_mul_f32_e32 v119, v119, v215
	v_mul_f32_e32 v120, v120, v215
	v_mul_f32_e32 v121, v121, v215
	v_mul_f32_e32 v114, v114, v215
	v_mul_f32_e32 v115, v115, v215
	v_mul_f32_e32 v116, v116, v215
	v_mul_f32_e32 v117, v117, v215
	v_exp_f32_e32 v118, v118
	v_exp_f32_e32 v119, v119
	v_exp_f32_e32 v120, v120
	v_exp_f32_e32 v121, v121
	v_exp_f32_e32 v114, v114
	v_exp_f32_e32 v115, v115
	v_exp_f32_e32 v116, v116
	v_exp_f32_e32 v117, v117
	v_add_f32_e32 v118, 1.0, v118
	v_add_f32_e32 v119, 1.0, v119
	v_add_f32_e32 v120, 1.0, v120
	s_waitcnt vmcnt(13)
	v_lshlrev_b32_e32 v126, 16, v130
	v_and_b32_e32 v127, 0xffff0000, v130
	v_lshlrev_b32_e32 v246, 16, v132
	v_and_b32_e32 v247, 0xffff0000, v132
	v_pk_mul_f32 v[126:127], v[186:187], v[126:127] op_sel_hi:[0,1]
	v_pk_mul_f32 v[246:247], v[186:187], v[246:247] op_sel_hi:[0,1]
	s_waitcnt vmcnt(12)
	v_lshlrev_b32_e32 v244, 16, v134
	v_and_b32_e32 v245, 0xffff0000, v134
	v_lshlrev_b32_e32 v248, 16, v136
	v_and_b32_e32 v249, 0xffff0000, v136
	s_waitcnt vmcnt(11)
	v_pk_mul_f32 v[126:127], v[126:127], v[162:163]
	s_waitcnt vmcnt(10)
	v_pk_mul_f32 v[138:139], v[246:247], v[166:167]
	v_pk_fma_f32 v[122:123], v[122:123], v[126:127], v[244:245]
	v_pk_fma_f32 v[126:127], v[124:125], v[138:139], v[248:249]
	v_add_f32_e32 v124, 1.0, v219
	v_rcp_f32_e32 v243, v124
	v_lshlrev_b32_e32 v124, 16, v131
	v_and_b32_e32 v125, 0xffff0000, v131
	v_pk_mul_f32 v[124:125], v[186:187], v[124:125] op_sel_hi:[0,1]
	v_lshlrev_b32_e32 v130, 16, v135
	v_and_b32_e32 v131, 0xffff0000, v135
	v_pk_mul_f32 v[124:125], v[124:125], v[164:165]
	v_add_f32_e32 v121, 1.0, v121
	v_pk_fma_f32 v[124:125], v[128:129], v[124:125], v[130:131]
	v_lshlrev_b32_e32 v128, 16, v133
	v_and_b32_e32 v129, 0xffff0000, v133
	v_pk_mul_f32 v[128:129], v[186:187], v[128:129] op_sel_hi:[0,1]
	v_lshlrev_b32_e32 v130, 16, v137
	v_and_b32_e32 v131, 0xffff0000, v137
	v_pk_mul_f32 v[128:129], v[128:129], v[168:169]
	v_add_f32_e32 v114, 1.0, v114
	v_pk_fma_f32 v[128:129], v[242:243], v[128:129], v[130:131]
	v_lshlrev_b64 v[130:131], 12, v[184:185]
	v_lshl_add_u64 v[130:131], s[48:49], 0, v[130:131]
	v_lshl_add_u64 v[130:131], v[130:131], 0, v[180:181]
	global_store_dwordx4 v[130:131], v[122:125], off
	global_store_dwordx4 v[130:131], v[126:129], off offset:16
	s_nop 0
	v_add_f32_e32 v115, 1.0, v115
	v_add_f32_e32 v116, 1.0, v116
	v_add_f32_e32 v117, 1.0, v117
	v_rcp_f32_e32 v132, v118
	v_rcp_f32_e32 v133, v119
	v_rcp_f32_e32 v136, v120
	v_rcp_f32_e32 v137, v121
	v_rcp_f32_e32 v134, v114
	v_rcp_f32_e32 v135, v115
	v_rcp_f32_e32 v138, v116
	v_rcp_f32_e32 v139, v117
	v_mul_f32_e32 v185, 0xbfb8aa3b, v216
	v_mul_f32_e32 v110, v110, v185
	v_mul_f32_e32 v111, v111, v185
	v_mul_f32_e32 v112, v112, v185
	v_mul_f32_e32 v113, v113, v185
	s_waitcnt vmcnt(9)
	v_lshlrev_b32_e32 v114, 16, v220
	v_and_b32_e32 v115, 0xffff0000, v220
	v_lshlrev_b32_e32 v118, 16, v221
	v_and_b32_e32 v119, 0xffff0000, v221
	v_lshlrev_b32_e32 v116, 16, v222
	v_and_b32_e32 v117, 0xffff0000, v222
	s_waitcnt vmcnt(8)
	v_lshlrev_b32_e32 v142, 16, v226
	v_and_b32_e32 v143, 0xffff0000, v226
	v_lshlrev_b32_e32 v120, 16, v223
	v_and_b32_e32 v121, 0xffff0000, v223
	v_lshlrev_b32_e32 v220, 16, v227
	v_and_b32_e32 v221, 0xffff0000, v227
	v_pk_mul_f32 v[222:223], v[186:187], v[114:115] op_sel_hi:[0,1]
	v_pk_mul_f32 v[226:227], v[186:187], v[118:119] op_sel_hi:[0,1]
	v_lshlrev_b32_e32 v140, 16, v224
	v_and_b32_e32 v141, 0xffff0000, v224
	v_lshlrev_b32_e32 v144, 16, v225
	v_and_b32_e32 v145, 0xffff0000, v225
	v_pk_mul_f32 v[224:225], v[186:187], v[116:117] op_sel_hi:[0,1]
	v_pk_mul_f32 v[242:243], v[186:187], v[120:121] op_sel_hi:[0,1]
	global_load_dwordx4 v[118:121], v[238:239], off offset:256 nt
	global_load_dwordx4 v[114:117], v[240:241], off offset:256
	v_mul_f32_e32 v106, v106, v185
	v_mul_f32_e32 v107, v107, v185
	v_mul_f32_e32 v108, v108, v185
	v_mul_f32_e32 v109, v109, v185
	v_exp_f32_e32 v110, v110
	v_exp_f32_e32 v111, v111
	v_exp_f32_e32 v112, v112
	v_exp_f32_e32 v113, v113
	v_exp_f32_e32 v106, v106
	v_exp_f32_e32 v107, v107
	v_exp_f32_e32 v108, v108
	v_exp_f32_e32 v109, v109
	v_add_f32_e32 v110, 1.0, v110
	v_add_f32_e32 v111, 1.0, v111
	v_add_f32_e32 v112, 1.0, v112
	v_add_f32_e32 v113, 1.0, v113
	v_add_f32_e32 v106, 1.0, v106
	v_add_f32_e32 v107, 1.0, v107
	v_add_f32_e32 v108, 1.0, v108
	v_add_f32_e32 v109, 1.0, v109
	v_mul_f32_e32 v102, v102, v185
	v_mul_f32_e32 v103, v103, v185
	v_mul_f32_e32 v104, v104, v185
	v_mul_f32_e32 v105, v105, v185
	v_mul_f32_e32 v98, v98, v185
	v_mul_f32_e32 v99, v99, v185
	v_mul_f32_e32 v100, v100, v185
	v_mul_f32_e32 v101, v101, v185
	v_exp_f32_e32 v102, v102
	v_exp_f32_e32 v103, v103
	v_exp_f32_e32 v104, v104
	v_exp_f32_e32 v105, v105
	v_exp_f32_e32 v98, v98
	v_exp_f32_e32 v99, v99
	v_exp_f32_e32 v100, v100
	v_exp_f32_e32 v101, v101
	v_add_f32_e32 v102, 1.0, v102
	v_add_f32_e32 v103, 1.0, v103
	v_add_f32_e32 v104, 1.0, v104
	v_add_f32_e32 v105, 1.0, v105
	v_add_f32_e32 v98, 1.0, v98
	v_pk_mul_f32 v[122:123], v[222:223], v[170:171]
	v_pk_mul_f32 v[124:125], v[226:227], v[172:173]
	v_pk_mul_f32 v[126:127], v[224:225], v[174:175]
	v_pk_fma_f32 v[122:123], v[132:133], v[122:123], v[140:141]
	v_pk_fma_f32 v[124:125], v[136:137], v[124:125], v[144:145]
	v_pk_mul_f32 v[128:129], v[242:243], v[176:177]
	v_pk_fma_f32 v[126:127], v[134:135], v[126:127], v[142:143]
	v_pk_fma_f32 v[128:129], v[138:139], v[128:129], v[220:221]
	global_store_dwordx4 v[130:131], v[122:125], off offset:512
	global_store_dwordx4 v[130:131], v[126:129], off offset:528
	s_nop 0
	v_or_b32_e32 v124, 48, v184
	v_rcp_f32_e32 v138, v110
	v_rcp_f32_e32 v139, v111
	v_rcp_f32_e32 v142, v112
	v_rcp_f32_e32 v143, v113
	v_ashrrev_i32_e32 v125, 31, v124
	v_rcp_f32_e32 v140, v106
	v_rcp_f32_e32 v141, v107
	v_rcp_f32_e32 v144, v108
	v_rcp_f32_e32 v145, v109
	s_waitcnt vmcnt(11)
	v_lshlrev_b32_e32 v106, 16, v228
	v_and_b32_e32 v107, 0xffff0000, v228
	v_lshlrev_b32_e32 v110, 16, v229
	v_and_b32_e32 v111, 0xffff0000, v229
	v_lshlrev_b64 v[122:123], 11, v[124:125]
	v_lshlrev_b64 v[134:135], 12, v[236:237]
	s_waitcnt vmcnt(9)
	v_lshlrev_b32_e32 v220, 16, v232
	v_and_b32_e32 v221, 0xffff0000, v232
	v_lshlrev_b32_e32 v108, 16, v230
	v_and_b32_e32 v109, 0xffff0000, v230
	v_lshlrev_b32_e32 v224, 16, v233
	v_and_b32_e32 v225, 0xffff0000, v233
	v_lshlrev_b32_e32 v112, 16, v231
	v_and_b32_e32 v113, 0xffff0000, v231
	v_pk_mul_f32 v[228:229], v[190:191], v[106:107] op_sel_hi:[0,1]
	v_pk_mul_f32 v[232:233], v[190:191], v[110:111] op_sel_hi:[0,1]
	v_lshl_add_u64 v[136:137], s[82:83], 0, v[122:123]
	v_lshl_add_u64 v[134:135], s[48:49], 0, v[134:135]
	v_lshlrev_b32_e32 v222, 16, v234
	v_and_b32_e32 v223, 0xffff0000, v234
	v_lshlrev_b32_e32 v226, 16, v235
	v_and_b32_e32 v227, 0xffff0000, v235
	v_pk_mul_f32 v[230:231], v[190:191], v[108:109] op_sel_hi:[0,1]
	v_pk_mul_f32 v[234:235], v[190:191], v[112:113] op_sel_hi:[0,1]
	v_lshl_add_u64 v[122:123], s[18:19], 0, v[122:123]
	v_lshl_add_u64 v[136:137], v[136:137], 0, v[182:183]
	v_lshl_add_u64 v[134:135], v[134:135], 0, v[180:181]
	v_lshl_add_u64 v[122:123], v[122:123], 0, v[182:183]
	global_load_dwordx4 v[110:113], v[136:137], off nt
	global_load_dwordx4 v[106:109], v[122:123], off
	v_add_f32_e32 v99, 1.0, v99
	v_add_f32_e32 v100, 1.0, v100
	v_add_f32_e32 v101, 1.0, v101
	v_mul_f32_e32 v185, 0xbfb8aa3b, v218
	v_mul_f32_e32 v94, v94, v185
	v_mul_f32_e32 v95, v95, v185
	v_mul_f32_e32 v96, v96, v185
	v_mul_f32_e32 v97, v97, v185
	v_mul_f32_e32 v90, v90, v185
	v_mul_f32_e32 v91, v91, v185
	v_mul_f32_e32 v92, v92, v185
	v_mul_f32_e32 v93, v93, v185
	v_exp_f32_e32 v94, v94
	v_exp_f32_e32 v95, v95
	v_exp_f32_e32 v96, v96
	v_exp_f32_e32 v97, v97
	v_exp_f32_e32 v90, v90
	v_exp_f32_e32 v91, v91
	v_exp_f32_e32 v92, v92
	v_exp_f32_e32 v93, v93
	v_add_f32_e32 v94, 1.0, v94
	v_add_f32_e32 v95, 1.0, v95
	v_add_f32_e32 v96, 1.0, v96
	v_add_f32_e32 v97, 1.0, v97
	v_add_f32_e32 v90, 1.0, v90
	v_add_f32_e32 v91, 1.0, v91
	v_add_f32_e32 v92, 1.0, v92
	v_add_f32_e32 v93, 1.0, v93
	v_mul_f32_e32 v86, v86, v185
	v_mul_f32_e32 v82, v82, v185
	v_mul_f32_e32 v87, v87, v185
	v_mul_f32_e32 v83, v83, v185
	v_mul_f32_e32 v88, v88, v185
	v_mul_f32_e32 v89, v89, v185
	v_mul_f32_e32 v84, v84, v185
	v_mul_f32_e32 v85, v85, v185
	v_exp_f32_e32 v86, v86
	v_exp_f32_e32 v82, v82
	v_exp_f32_e32 v87, v87
	v_pk_mul_f32 v[126:127], v[228:229], v[162:163]
	v_pk_mul_f32 v[128:129], v[232:233], v[164:165]
	v_pk_mul_f32 v[130:131], v[230:231], v[166:167]
	v_pk_mul_f32 v[132:133], v[234:235], v[168:169]
	v_pk_fma_f32 v[126:127], v[138:139], v[126:127], v[220:221]
	v_pk_fma_f32 v[128:129], v[142:143], v[128:129], v[224:225]
	v_pk_fma_f32 v[130:131], v[140:141], v[130:131], v[222:223]
	v_pk_fma_f32 v[132:133], v[144:145], v[132:133], v[226:227]
	global_store_dwordx4 v[134:135], v[126:129], off
	global_store_dwordx4 v[134:135], v[130:133], off offset:16
	s_nop 0
	v_rcp_f32_e32 v138, v102
	v_rcp_f32_e32 v139, v103
	v_rcp_f32_e32 v142, v104
	v_rcp_f32_e32 v143, v105
	v_rcp_f32_e32 v140, v98
	v_rcp_f32_e32 v141, v99
	v_rcp_f32_e32 v144, v100
	v_rcp_f32_e32 v145, v101
	v_lshlrev_b32_e32 v98, 16, v154
	v_and_b32_e32 v99, 0xffff0000, v154
	v_lshlrev_b32_e32 v102, 16, v155
	v_and_b32_e32 v103, 0xffff0000, v155
	s_waitcnt vmcnt(12)
	v_lshlrev_b32_e32 v220, 16, v158
	v_and_b32_e32 v221, 0xffff0000, v158
	v_lshlrev_b32_e32 v100, 16, v156
	v_and_b32_e32 v101, 0xffff0000, v156
	v_lshlrev_b32_e32 v154, 16, v159
	v_and_b32_e32 v155, 0xffff0000, v159
	v_lshlrev_b32_e32 v104, 16, v157
	v_and_b32_e32 v105, 0xffff0000, v157
	v_pk_mul_f32 v[158:159], v[190:191], v[98:99] op_sel_hi:[0,1]
	v_pk_mul_f32 v[224:225], v[190:191], v[102:103] op_sel_hi:[0,1]
	v_lshlrev_b32_e32 v222, 16, v160
	v_and_b32_e32 v223, 0xffff0000, v160
	v_lshlrev_b32_e32 v156, 16, v161
	v_and_b32_e32 v157, 0xffff0000, v161
	v_pk_mul_f32 v[160:161], v[190:191], v[100:101] op_sel_hi:[0,1]
	v_pk_mul_f32 v[226:227], v[190:191], v[104:105] op_sel_hi:[0,1]
	global_load_dwordx4 v[102:105], v[136:137], off offset:256 nt
	global_load_dwordx4 v[98:101], v[122:123], off offset:256
	v_lshlrev_b64 v[136:137], 12, v[194:195]
	v_lshl_add_u64 v[136:137], s[48:49], 0, v[136:137]
	v_lshl_add_u64 v[136:137], v[136:137], 0, v[180:181]
	v_exp_f32_e32 v83, v83
	v_exp_f32_e32 v88, v88
	v_exp_f32_e32 v89, v89
	v_exp_f32_e32 v84, v84
	v_exp_f32_e32 v85, v85
	v_add_f32_e32 v86, 1.0, v86
	v_add_f32_e32 v82, 1.0, v82
	v_add_f32_e32 v87, 1.0, v87
	v_add_f32_e32 v83, 1.0, v83
	v_add_f32_e32 v88, 1.0, v88
	v_add_f32_e32 v89, 1.0, v89
	v_add_f32_e32 v84, 1.0, v84
	v_add_f32_e32 v85, 1.0, v85
	v_lshlrev_b64 v[124:125], 12, v[124:125]
	v_lshl_add_u64 v[124:125], s[48:49], 0, v[124:125]
	v_lshl_add_u64 v[124:125], v[124:125], 0, v[180:181]
	s_and_b64 vcc, exec, s[4:5]
	s_mov_b32 s24, s6
	s_mov_b32 s26, s8
	s_mov_b64 s[30:31], s[22:23]
	s_mov_b64 s[28:29], s[20:21]
	v_readlane_b32 s52, v251, 10
	v_readlane_b32 s53, v251, 11
	v_readlane_b32 s54, v251, 12
	v_readlane_b32 s55, v251, 13
	v_readlane_b32 s56, v251, 14
	v_readlane_b32 s57, v251, 15
	s_mov_b64 s[50:51], s[62:63]
	v_pk_mul_f32 v[122:123], v[158:159], v[170:171]
	v_pk_mul_f32 v[128:129], v[224:225], v[172:173]
	v_pk_mul_f32 v[130:131], v[160:161], v[174:175]
	v_pk_mul_f32 v[132:133], v[226:227], v[176:177]
	v_pk_fma_f32 v[126:127], v[138:139], v[122:123], v[220:221]
	v_pk_fma_f32 v[128:129], v[142:143], v[128:129], v[154:155]
	v_pk_fma_f32 v[130:131], v[140:141], v[130:131], v[222:223]
	v_pk_fma_f32 v[132:133], v[144:145], v[132:133], v[156:157]
	global_store_dwordx4 v[134:135], v[126:129], off offset:512
	global_store_dwordx4 v[134:135], v[130:133], off offset:528
	s_nop 0
	v_add_u32_e32 v122, 0x80, v184
	v_rcp_f32_e32 v140, v94
	v_rcp_f32_e32 v141, v95
	v_rcp_f32_e32 v144, v96
	v_rcp_f32_e32 v145, v97
	v_ashrrev_i32_e32 v123, 31, v122
	v_rcp_f32_e32 v142, v90
	v_rcp_f32_e32 v143, v91
	v_rcp_f32_e32 v154, v92
	v_rcp_f32_e32 v155, v93
	s_waitcnt vmcnt(15)
	v_lshlrev_b32_e32 v90, 16, v150
	v_and_b32_e32 v91, 0xffff0000, v150
	v_lshlrev_b32_e32 v94, 16, v151
	v_and_b32_e32 v95, 0xffff0000, v151
	v_lshlrev_b64 v[134:135], 11, v[122:123]
	v_lshlrev_b32_e32 v92, 16, v152
	v_and_b32_e32 v93, 0xffff0000, v152
	v_lshlrev_b32_e32 v96, 16, v153
	v_and_b32_e32 v97, 0xffff0000, v153
	v_pk_mul_f32 v[150:151], v[192:193], v[90:91] op_sel_hi:[0,1]
	v_pk_mul_f32 v[160:161], v[192:193], v[94:95] op_sel_hi:[0,1]
	v_lshl_add_u64 v[138:139], s[82:83], 0, v[134:135]
	s_waitcnt vmcnt(14)
	v_lshlrev_b32_e32 v156, 16, v146
	v_and_b32_e32 v157, 0xffff0000, v146
	v_lshlrev_b32_e32 v146, 16, v147
	v_and_b32_e32 v147, 0xffff0000, v147
	v_pk_mul_f32 v[152:153], v[192:193], v[92:93] op_sel_hi:[0,1]
	v_pk_mul_f32 v[194:195], v[192:193], v[96:97] op_sel_hi:[0,1]
	v_lshl_add_u64 v[134:135], s[18:19], 0, v[134:135]
	v_lshl_add_u64 v[138:139], v[138:139], 0, v[182:183]
	v_lshlrev_b32_e32 v158, 16, v148
	v_and_b32_e32 v159, 0xffff0000, v148
	v_lshlrev_b32_e32 v148, 16, v149
	v_and_b32_e32 v149, 0xffff0000, v149
	v_lshl_add_u64 v[134:135], v[134:135], 0, v[182:183]
	global_load_dwordx4 v[94:97], v[138:139], off nt
	global_load_dwordx4 v[90:93], v[134:135], off
	v_pk_mul_f32 v[126:127], v[150:151], v[162:163]
	v_pk_mul_f32 v[128:129], v[160:161], v[164:165]
	v_pk_mul_f32 v[130:131], v[152:153], v[166:167]
	v_pk_mul_f32 v[132:133], v[194:195], v[168:169]
	v_pk_fma_f32 v[126:127], v[140:141], v[126:127], v[156:157]
	v_pk_fma_f32 v[128:129], v[144:145], v[128:129], v[146:147]
	v_pk_fma_f32 v[130:131], v[142:143], v[130:131], v[158:159]
	v_pk_fma_f32 v[132:133], v[154:155], v[132:133], v[148:149]
	global_store_dwordx4 v[136:137], v[126:129], off
	global_store_dwordx4 v[136:137], v[130:133], off offset:16
	s_nop 0
	v_rcp_f32_e32 v140, v86
	v_rcp_f32_e32 v142, v82
	v_rcp_f32_e32 v141, v87
	v_rcp_f32_e32 v143, v83
	v_rcp_f32_e32 v144, v88
	v_rcp_f32_e32 v145, v89
	v_rcp_f32_e32 v146, v84
	v_rcp_f32_e32 v147, v85
	s_waitcnt vmcnt(15)
	v_lshlrev_b32_e32 v82, 16, v118
	v_and_b32_e32 v83, 0xffff0000, v118
	v_lshlrev_b32_e32 v84, 16, v120
	v_and_b32_e32 v85, 0xffff0000, v120
	v_lshlrev_b32_e32 v86, 16, v119
	v_and_b32_e32 v87, 0xffff0000, v119
	s_waitcnt vmcnt(14)
	v_lshlrev_b32_e32 v148, 16, v114
	v_and_b32_e32 v149, 0xffff0000, v114
	v_lshlrev_b32_e32 v150, 16, v116
	v_and_b32_e32 v151, 0xffff0000, v116
	v_lshlrev_b32_e32 v152, 16, v115
	v_and_b32_e32 v153, 0xffff0000, v115
	v_lshlrev_b32_e32 v88, 16, v121
	v_and_b32_e32 v89, 0xffff0000, v121
	v_lshlrev_b32_e32 v120, 16, v117
	v_and_b32_e32 v121, 0xffff0000, v117
	v_pk_mul_f32 v[114:115], v[192:193], v[82:83] op_sel_hi:[0,1]
	v_pk_mul_f32 v[116:117], v[192:193], v[84:85] op_sel_hi:[0,1]
	v_pk_mul_f32 v[118:119], v[192:193], v[86:87] op_sel_hi:[0,1]
	v_pk_mul_f32 v[154:155], v[192:193], v[88:89] op_sel_hi:[0,1]
	global_load_dwordx4 v[86:89], v[138:139], off offset:256 nt
	global_load_dwordx4 v[82:85], v[134:135], off offset:256
	v_pk_mul_f32 v[114:115], v[114:115], v[170:171]
	v_pk_mul_f32 v[116:117], v[116:117], v[174:175]
	v_pk_mul_f32 v[126:127], v[118:119], v[172:173]
	v_pk_mul_f32 v[128:129], v[154:155], v[176:177]
	v_pk_fma_f32 v[114:115], v[140:141], v[114:115], v[148:149]
	v_pk_fma_f32 v[118:119], v[142:143], v[116:117], v[150:151]
	v_pk_fma_f32 v[116:117], v[144:145], v[126:127], v[152:153]
	v_pk_fma_f32 v[120:121], v[146:147], v[128:129], v[120:121]
	global_store_dwordx4 v[136:137], v[114:117], off offset:512
	global_store_dwordx4 v[136:137], v[118:121], off offset:528
	s_nop 0
	v_mul_f32_e32 v148, 0xbfb8aa3b, v217
	v_mul_f32_e32 v78, v78, v148
	v_mul_f32_e32 v74, v74, v148
	v_mul_f32_e32 v79, v79, v148
	v_mul_f32_e32 v75, v75, v148
	v_mul_f32_e32 v80, v80, v148
	v_mul_f32_e32 v81, v81, v148
	v_mul_f32_e32 v76, v76, v148
	v_mul_f32_e32 v77, v77, v148
	v_exp_f32_e32 v78, v78
	v_exp_f32_e32 v74, v74
	v_exp_f32_e32 v79, v79
	v_exp_f32_e32 v75, v75
	v_exp_f32_e32 v80, v80
	v_exp_f32_e32 v81, v81
	v_exp_f32_e32 v76, v76
	v_exp_f32_e32 v77, v77
	v_add_f32_e32 v78, 1.0, v78
	v_add_f32_e32 v74, 1.0, v74
	v_add_f32_e32 v79, 1.0, v79
	v_add_f32_e32 v75, 1.0, v75
	v_add_f32_e32 v80, 1.0, v80
	v_add_f32_e32 v81, 1.0, v81
	v_add_u32_e32 v114, 0x90, v184
	v_add_f32_e32 v76, 1.0, v76
	v_add_f32_e32 v77, 1.0, v77
	v_rcp_f32_e32 v132, v78
	v_rcp_f32_e32 v134, v74
	v_rcp_f32_e32 v133, v79
	v_rcp_f32_e32 v135, v75
	v_rcp_f32_e32 v136, v80
	v_rcp_f32_e32 v137, v81
	v_ashrrev_i32_e32 v115, 31, v114
	v_rcp_f32_e32 v138, v76
	v_rcp_f32_e32 v139, v77
	s_waitcnt vmcnt(15)
	v_lshlrev_b32_e32 v74, 16, v110
	v_and_b32_e32 v75, 0xffff0000, v110
	v_lshlrev_b32_e32 v76, 16, v112
	v_and_b32_e32 v77, 0xffff0000, v112
	v_lshlrev_b32_e32 v78, 16, v111
	v_and_b32_e32 v79, 0xffff0000, v111
	v_lshlrev_b64 v[120:121], 11, v[114:115]
	s_waitcnt vmcnt(14)
	v_lshlrev_b32_e32 v140, 16, v106
	v_and_b32_e32 v141, 0xffff0000, v106
	v_lshlrev_b32_e32 v142, 16, v108
	v_and_b32_e32 v143, 0xffff0000, v108
	v_lshlrev_b32_e32 v144, 16, v107
	v_and_b32_e32 v145, 0xffff0000, v107
	v_lshlrev_b32_e32 v80, 16, v113
	v_and_b32_e32 v81, 0xffff0000, v113
	v_lshlrev_b32_e32 v112, 16, v109
	v_and_b32_e32 v113, 0xffff0000, v109
	v_pk_mul_f32 v[106:107], v[188:189], v[74:75] op_sel_hi:[0,1]
	v_pk_mul_f32 v[108:109], v[188:189], v[76:77] op_sel_hi:[0,1]
	v_pk_mul_f32 v[110:111], v[188:189], v[78:79] op_sel_hi:[0,1]
	v_lshl_add_u64 v[130:131], s[82:83], 0, v[120:121]
	v_pk_mul_f32 v[146:147], v[188:189], v[80:81] op_sel_hi:[0,1]
	v_lshl_add_u64 v[120:121], s[18:19], 0, v[120:121]
	v_lshl_add_u64 v[130:131], v[130:131], 0, v[182:183]
	v_lshl_add_u64 v[120:121], v[120:121], 0, v[182:183]
	global_load_dwordx4 v[78:81], v[130:131], off nt
	global_load_dwordx4 v[74:77], v[120:121], off
	v_mul_f32_e32 v70, v70, v148
	v_mul_f32_e32 v66, v66, v148
	v_mul_f32_e32 v71, v71, v148
	v_mul_f32_e32 v67, v67, v148
	v_mul_f32_e32 v72, v72, v148
	v_mul_f32_e32 v73, v73, v148
	v_mul_f32_e32 v68, v68, v148
	v_mul_f32_e32 v69, v69, v148
	v_exp_f32_e32 v70, v70
	v_exp_f32_e32 v66, v66
	v_exp_f32_e32 v71, v71
	v_exp_f32_e32 v67, v67
	v_exp_f32_e32 v72, v72
	v_exp_f32_e32 v73, v73
	v_exp_f32_e32 v68, v68
	v_exp_f32_e32 v69, v69
	v_add_f32_e32 v70, 1.0, v70
	v_pk_mul_f32 v[106:107], v[106:107], v[162:163]
	v_pk_mul_f32 v[108:109], v[108:109], v[166:167]
	v_pk_mul_f32 v[116:117], v[110:111], v[164:165]
	v_pk_mul_f32 v[118:119], v[146:147], v[168:169]
	v_pk_fma_f32 v[106:107], v[132:133], v[106:107], v[140:141]
	v_pk_fma_f32 v[110:111], v[134:135], v[108:109], v[142:143]
	v_pk_fma_f32 v[108:109], v[136:137], v[116:117], v[144:145]
	v_pk_fma_f32 v[112:113], v[138:139], v[118:119], v[112:113]
	global_store_dwordx4 v[124:125], v[106:109], off
	global_store_dwordx4 v[124:125], v[110:113], off offset:16
	s_nop 0
	v_add_f32_e32 v66, 1.0, v66
	v_add_f32_e32 v71, 1.0, v71
	v_add_f32_e32 v67, 1.0, v67
	v_add_f32_e32 v72, 1.0, v72
	v_add_f32_e32 v73, 1.0, v73
	v_add_f32_e32 v68, 1.0, v68
	v_add_f32_e32 v69, 1.0, v69
	v_rcp_f32_e32 v116, v70
	v_rcp_f32_e32 v118, v66
	v_rcp_f32_e32 v117, v71
	v_rcp_f32_e32 v119, v67
	v_rcp_f32_e32 v126, v72
	v_rcp_f32_e32 v127, v73
	v_rcp_f32_e32 v128, v68
	v_rcp_f32_e32 v129, v69
	s_waitcnt vmcnt(15)
	v_lshlrev_b32_e32 v66, 16, v102
	v_and_b32_e32 v67, 0xffff0000, v102
	v_lshlrev_b32_e32 v68, 16, v104
	v_and_b32_e32 v69, 0xffff0000, v104
	v_lshlrev_b32_e32 v70, 16, v103
	v_and_b32_e32 v71, 0xffff0000, v103
	s_waitcnt vmcnt(14)
	v_lshlrev_b32_e32 v132, 16, v98
	v_and_b32_e32 v133, 0xffff0000, v98
	v_lshlrev_b32_e32 v134, 16, v100
	v_and_b32_e32 v135, 0xffff0000, v100
	v_lshlrev_b32_e32 v136, 16, v99
	v_and_b32_e32 v137, 0xffff0000, v99
	v_lshlrev_b32_e32 v72, 16, v105
	v_and_b32_e32 v73, 0xffff0000, v105
	v_lshlrev_b32_e32 v104, 16, v101
	v_and_b32_e32 v105, 0xffff0000, v101
	v_pk_mul_f32 v[98:99], v[188:189], v[66:67] op_sel_hi:[0,1]
	v_pk_mul_f32 v[100:101], v[188:189], v[68:69] op_sel_hi:[0,1]
	v_pk_mul_f32 v[102:103], v[188:189], v[70:71] op_sel_hi:[0,1]
	v_pk_mul_f32 v[138:139], v[188:189], v[72:73] op_sel_hi:[0,1]
	global_load_dwordx4 v[70:73], v[130:131], off offset:256 nt
	global_load_dwordx4 v[66:69], v[120:121], off offset:256
	v_lshlrev_b64 v[120:121], 12, v[122:123]
	v_lshl_add_u64 v[120:121], s[48:49], 0, v[120:121]
	v_lshl_add_u64 v[120:121], v[120:121], 0, v[180:181]
	v_pk_mul_f32 v[98:99], v[98:99], v[170:171]
	v_pk_mul_f32 v[100:101], v[100:101], v[174:175]
	v_pk_mul_f32 v[106:107], v[102:103], v[172:173]
	v_pk_mul_f32 v[108:109], v[138:139], v[176:177]
	v_pk_fma_f32 v[98:99], v[116:117], v[98:99], v[132:133]
	v_pk_fma_f32 v[102:103], v[118:119], v[100:101], v[134:135]
	v_pk_fma_f32 v[100:101], v[126:127], v[106:107], v[136:137]
	v_pk_fma_f32 v[104:105], v[128:129], v[108:109], v[104:105]
	global_store_dwordx4 v[124:125], v[98:101], off offset:512
	global_store_dwordx4 v[124:125], v[102:105], off offset:528
	s_nop 0
	ds_read_b32 v107, v203
	ds_read_b32 v106, v204
	ds_read_b32 v109, v205
	ds_read_b32 v110, v206
	ds_read_b32 v113, v207
	ds_read_b32 v112, v208
	ds_read_b32 v111, v209
	ds_read_b32 v108, v210
	s_waitcnt lgkmcnt(7)
	v_mul_f32_e32 v107, 0xbfb8aa3b, v107
	v_mul_f32_e32 v62, v62, v107
	v_mul_f32_e32 v58, v58, v107
	v_mul_f32_e32 v63, v63, v107
	v_mul_f32_e32 v59, v59, v107
	v_mul_f32_e32 v64, v64, v107
	v_mul_f32_e32 v65, v65, v107
	v_mul_f32_e32 v60, v60, v107
	v_mul_f32_e32 v61, v61, v107
	v_exp_f32_e32 v62, v62
	v_exp_f32_e32 v58, v58
	v_exp_f32_e32 v63, v63
	v_exp_f32_e32 v59, v59
	v_exp_f32_e32 v64, v64
	v_exp_f32_e32 v65, v65
	v_exp_f32_e32 v60, v60
	v_exp_f32_e32 v61, v61
	v_add_f32_e32 v62, 1.0, v62
	v_add_f32_e32 v58, 1.0, v58
	v_add_f32_e32 v63, 1.0, v63
	v_add_f32_e32 v59, 1.0, v59
	v_add_f32_e32 v64, 1.0, v64
	v_add_f32_e32 v65, 1.0, v65
	v_add_u32_e32 v116, 0xa0, v184
	v_add_f32_e32 v60, 1.0, v60
	v_add_f32_e32 v61, 1.0, v61
	v_rcp_f32_e32 v124, v62
	v_rcp_f32_e32 v126, v58
	v_rcp_f32_e32 v125, v63
	v_rcp_f32_e32 v127, v59
	v_rcp_f32_e32 v128, v64
	v_rcp_f32_e32 v129, v65
	v_ashrrev_i32_e32 v117, 31, v116
	v_rcp_f32_e32 v130, v60
	v_rcp_f32_e32 v131, v61
	s_waitcnt vmcnt(15)
	v_lshlrev_b32_e32 v58, 16, v94
	v_and_b32_e32 v59, 0xffff0000, v94
	v_lshlrev_b32_e32 v60, 16, v96
	v_and_b32_e32 v61, 0xffff0000, v96
	v_lshlrev_b32_e32 v62, 16, v95
	v_and_b32_e32 v63, 0xffff0000, v95
	v_lshlrev_b64 v[118:119], 11, v[116:117]
	s_waitcnt vmcnt(14)
	v_lshlrev_b32_e32 v132, 16, v90
	v_and_b32_e32 v133, 0xffff0000, v90
	v_lshlrev_b32_e32 v134, 16, v92
	v_and_b32_e32 v135, 0xffff0000, v92
	v_lshlrev_b32_e32 v136, 16, v91
	v_and_b32_e32 v137, 0xffff0000, v91
	v_lshlrev_b32_e32 v64, 16, v97
	v_and_b32_e32 v65, 0xffff0000, v97
	v_lshlrev_b32_e32 v96, 16, v93
	v_and_b32_e32 v97, 0xffff0000, v93
	s_waitcnt lgkmcnt(6)
	v_pk_mul_f32 v[90:91], v[106:107], v[58:59] op_sel_hi:[0,1]
	v_pk_mul_f32 v[92:93], v[106:107], v[60:61] op_sel_hi:[0,1]
	v_pk_mul_f32 v[94:95], v[106:107], v[62:63] op_sel_hi:[0,1]
	v_lshl_add_u64 v[122:123], s[82:83], 0, v[118:119]
	v_pk_mul_f32 v[138:139], v[106:107], v[64:65] op_sel_hi:[0,1]
	v_lshl_add_u64 v[118:119], s[18:19], 0, v[118:119]
	v_lshl_add_u64 v[122:123], v[122:123], 0, v[182:183]
	v_lshl_add_u64 v[118:119], v[118:119], 0, v[182:183]
	global_load_dwordx4 v[62:65], v[122:123], off nt
	global_load_dwordx4 v[58:61], v[118:119], off
	v_mul_f32_e32 v54, v54, v107
	v_mul_f32_e32 v50, v50, v107
	v_mul_f32_e32 v55, v55, v107
	v_mul_f32_e32 v51, v51, v107
	v_mul_f32_e32 v56, v56, v107
	v_mul_f32_e32 v57, v57, v107
	v_mul_f32_e32 v52, v52, v107
	v_mul_f32_e32 v53, v53, v107
	v_exp_f32_e32 v54, v54
	v_exp_f32_e32 v50, v50
	v_exp_f32_e32 v55, v55
	v_exp_f32_e32 v51, v51
	v_exp_f32_e32 v56, v56
	v_exp_f32_e32 v57, v57
	v_exp_f32_e32 v52, v52
	v_exp_f32_e32 v53, v53
	v_pk_mul_f32 v[90:91], v[90:91], v[162:163]
	v_pk_mul_f32 v[92:93], v[92:93], v[166:167]
	v_pk_mul_f32 v[98:99], v[94:95], v[164:165]
	v_pk_mul_f32 v[100:101], v[138:139], v[168:169]
	v_pk_fma_f32 v[90:91], v[124:125], v[90:91], v[132:133]
	v_pk_fma_f32 v[94:95], v[126:127], v[92:93], v[134:135]
	v_pk_fma_f32 v[92:93], v[128:129], v[98:99], v[136:137]
	v_pk_fma_f32 v[96:97], v[130:131], v[100:101], v[96:97]
	global_store_dwordx4 v[120:121], v[90:93], off
	global_store_dwordx4 v[120:121], v[94:97], off offset:16
	s_nop 0
	v_add_f32_e32 v54, 1.0, v54
	v_add_f32_e32 v50, 1.0, v50
	v_add_f32_e32 v55, 1.0, v55
	v_add_f32_e32 v51, 1.0, v51
	v_add_f32_e32 v56, 1.0, v56
	v_add_f32_e32 v57, 1.0, v57
	v_add_f32_e32 v52, 1.0, v52
	v_add_f32_e32 v53, 1.0, v53
	v_rcp_f32_e32 v98, v54
	v_rcp_f32_e32 v100, v50
	v_rcp_f32_e32 v99, v55
	v_rcp_f32_e32 v101, v51
	v_rcp_f32_e32 v102, v56
	v_rcp_f32_e32 v103, v57
	v_rcp_f32_e32 v104, v52
	v_rcp_f32_e32 v105, v53
	s_waitcnt vmcnt(15)
	v_lshlrev_b32_e32 v50, 16, v86
	v_and_b32_e32 v51, 0xffff0000, v86
	v_lshlrev_b32_e32 v52, 16, v88
	v_and_b32_e32 v53, 0xffff0000, v88
	v_lshlrev_b32_e32 v54, 16, v87
	v_and_b32_e32 v55, 0xffff0000, v87
	s_waitcnt vmcnt(14)
	v_lshlrev_b32_e32 v124, 16, v82
	v_and_b32_e32 v125, 0xffff0000, v82
	v_lshlrev_b32_e32 v126, 16, v84
	v_and_b32_e32 v127, 0xffff0000, v84
	v_lshlrev_b32_e32 v128, 16, v83
	v_and_b32_e32 v129, 0xffff0000, v83
	v_lshlrev_b32_e32 v56, 16, v89
	v_and_b32_e32 v57, 0xffff0000, v89
	v_lshlrev_b32_e32 v88, 16, v85
	v_and_b32_e32 v89, 0xffff0000, v85
	v_pk_mul_f32 v[82:83], v[106:107], v[50:51] op_sel_hi:[0,1]
	v_pk_mul_f32 v[84:85], v[106:107], v[52:53] op_sel_hi:[0,1]
	v_pk_mul_f32 v[86:87], v[106:107], v[54:55] op_sel_hi:[0,1]
	v_pk_mul_f32 v[106:107], v[106:107], v[56:57] op_sel_hi:[0,1]
	global_load_dwordx4 v[54:57], v[122:123], off offset:256 nt
	global_load_dwordx4 v[50:53], v[118:119], off offset:256
	s_waitcnt lgkmcnt(5)
	v_mul_f32_e32 v109, 0xbfb8aa3b, v109
	v_mul_f32_e32 v46, v46, v109
	v_mul_f32_e32 v42, v42, v109
	v_mul_f32_e32 v47, v47, v109
	v_mul_f32_e32 v43, v43, v109
	v_mul_f32_e32 v48, v48, v109
	v_mul_f32_e32 v49, v49, v109
	v_mul_f32_e32 v44, v44, v109
	v_mul_f32_e32 v45, v45, v109
	v_exp_f32_e32 v46, v46
	v_exp_f32_e32 v42, v42
	v_exp_f32_e32 v47, v47
	v_exp_f32_e32 v43, v43
	v_exp_f32_e32 v48, v48
	v_exp_f32_e32 v49, v49
	v_exp_f32_e32 v44, v44
	v_exp_f32_e32 v45, v45
	v_add_f32_e32 v46, 1.0, v46
	v_add_f32_e32 v42, 1.0, v42
	v_add_f32_e32 v47, 1.0, v47
	v_add_f32_e32 v43, 1.0, v43
	v_add_f32_e32 v48, 1.0, v48
	v_add_f32_e32 v49, 1.0, v49
	v_add_f32_e32 v44, 1.0, v44
	v_add_f32_e32 v45, 1.0, v45
	s_waitcnt vmcnt(12)
	v_lshlrev_b32_e32 v118, 16, v75
	v_and_b32_e32 v119, 0xffff0000, v75
	v_mul_f32_e32 v38, v38, v109
	v_mul_f32_e32 v34, v34, v109
	v_mul_f32_e32 v39, v39, v109
	v_mul_f32_e32 v35, v35, v109
	v_mul_f32_e32 v40, v40, v109
	v_mul_f32_e32 v41, v41, v109
	v_mul_f32_e32 v36, v36, v109
	v_mul_f32_e32 v37, v37, v109
	v_exp_f32_e32 v38, v38
	v_exp_f32_e32 v34, v34
	v_exp_f32_e32 v39, v39
	v_exp_f32_e32 v35, v35
	v_exp_f32_e32 v40, v40
	v_exp_f32_e32 v41, v41
	v_pk_mul_f32 v[82:83], v[82:83], v[170:171]
	v_pk_mul_f32 v[84:85], v[84:85], v[174:175]
	v_pk_mul_f32 v[90:91], v[86:87], v[172:173]
	v_pk_mul_f32 v[92:93], v[106:107], v[176:177]
	v_pk_fma_f32 v[82:83], v[98:99], v[82:83], v[124:125]
	v_pk_fma_f32 v[86:87], v[100:101], v[84:85], v[126:127]
	v_pk_fma_f32 v[84:85], v[102:103], v[90:91], v[128:129]
	v_pk_fma_f32 v[88:89], v[104:105], v[92:93], v[88:89]
	global_store_dwordx4 v[120:121], v[82:85], off offset:512
	global_store_dwordx4 v[120:121], v[86:89], off offset:528
	s_nop 0
	v_add_u32_e32 v82, 0xb0, v184
	v_rcp_f32_e32 v98, v46
	v_rcp_f32_e32 v100, v42
	v_rcp_f32_e32 v99, v47
	v_rcp_f32_e32 v101, v43
	v_rcp_f32_e32 v102, v48
	v_rcp_f32_e32 v103, v49
	v_ashrrev_i32_e32 v83, 31, v82
	v_rcp_f32_e32 v104, v44
	v_rcp_f32_e32 v105, v45
	v_lshlrev_b32_e32 v42, 16, v78
	v_and_b32_e32 v43, 0xffff0000, v78
	v_lshlrev_b32_e32 v44, 16, v80
	v_and_b32_e32 v45, 0xffff0000, v80
	v_lshlrev_b32_e32 v46, 16, v79
	v_and_b32_e32 v47, 0xffff0000, v79
	v_lshlrev_b64 v[92:93], 11, v[82:83]
	v_lshlrev_b64 v[94:95], 12, v[114:115]
	v_lshlrev_b32_e32 v106, 16, v74
	v_and_b32_e32 v107, 0xffff0000, v74
	v_lshlrev_b32_e32 v114, 16, v76
	v_and_b32_e32 v115, 0xffff0000, v76
	v_lshlrev_b32_e32 v48, 16, v81
	v_and_b32_e32 v49, 0xffff0000, v81
	v_lshlrev_b32_e32 v80, 16, v77
	v_and_b32_e32 v81, 0xffff0000, v77
	s_waitcnt lgkmcnt(1)
	v_pk_mul_f32 v[74:75], v[110:111], v[42:43] op_sel_hi:[0,1]
	v_pk_mul_f32 v[76:77], v[110:111], v[44:45] op_sel_hi:[0,1]
	v_pk_mul_f32 v[78:79], v[110:111], v[46:47] op_sel_hi:[0,1]
	v_lshl_add_u64 v[96:97], s[82:83], 0, v[92:93]
	v_lshl_add_u64 v[94:95], s[48:49], 0, v[94:95]
	v_pk_mul_f32 v[120:121], v[110:111], v[48:49] op_sel_hi:[0,1]
	v_lshl_add_u64 v[92:93], s[18:19], 0, v[92:93]
	v_lshl_add_u64 v[96:97], v[96:97], 0, v[182:183]
	v_lshl_add_u64 v[94:95], v[94:95], 0, v[180:181]
	v_lshl_add_u64 v[92:93], v[92:93], 0, v[182:183]
	global_load_dwordx4 v[46:49], v[96:97], off nt
	global_load_dwordx4 v[42:45], v[92:93], off
	v_exp_f32_e32 v36, v36
	v_exp_f32_e32 v37, v37
	v_add_f32_e32 v38, 1.0, v38
	v_add_f32_e32 v34, 1.0, v34
	v_add_f32_e32 v39, 1.0, v39
	v_add_f32_e32 v35, 1.0, v35
	v_add_f32_e32 v40, 1.0, v40
	v_add_f32_e32 v41, 1.0, v41
	v_add_f32_e32 v36, 1.0, v36
	v_add_f32_e32 v37, 1.0, v37
	v_pk_mul_f32 v[74:75], v[74:75], v[162:163]
	v_pk_mul_f32 v[76:77], v[76:77], v[166:167]
	v_pk_mul_f32 v[84:85], v[78:79], v[164:165]
	v_pk_mul_f32 v[86:87], v[120:121], v[168:169]
	v_pk_fma_f32 v[74:75], v[98:99], v[74:75], v[106:107]
	v_pk_fma_f32 v[78:79], v[100:101], v[76:77], v[114:115]
	v_pk_fma_f32 v[76:77], v[102:103], v[84:85], v[118:119]
	v_pk_fma_f32 v[80:81], v[104:105], v[86:87], v[80:81]
	global_store_dwordx4 v[94:95], v[74:77], off
	global_store_dwordx4 v[94:95], v[78:81], off offset:16
	s_nop 0
	v_rcp_f32_e32 v84, v38
	v_rcp_f32_e32 v86, v34
	v_rcp_f32_e32 v85, v39
	v_rcp_f32_e32 v87, v35
	v_rcp_f32_e32 v88, v40
	v_rcp_f32_e32 v89, v41
	v_rcp_f32_e32 v90, v36
	v_rcp_f32_e32 v91, v37
	s_waitcnt vmcnt(15)
	v_lshlrev_b32_e32 v34, 16, v70
	v_and_b32_e32 v35, 0xffff0000, v70
	v_lshlrev_b32_e32 v36, 16, v72
	v_and_b32_e32 v37, 0xffff0000, v72
	v_lshlrev_b32_e32 v38, 16, v71
	v_and_b32_e32 v39, 0xffff0000, v71
	s_waitcnt vmcnt(14)
	v_lshlrev_b32_e32 v98, 16, v66
	v_and_b32_e32 v99, 0xffff0000, v66
	v_lshlrev_b32_e32 v100, 16, v68
	v_and_b32_e32 v101, 0xffff0000, v68
	v_lshlrev_b32_e32 v102, 16, v67
	v_and_b32_e32 v103, 0xffff0000, v67
	v_lshlrev_b32_e32 v40, 16, v73
	v_and_b32_e32 v41, 0xffff0000, v73
	v_lshlrev_b32_e32 v72, 16, v69
	v_and_b32_e32 v73, 0xffff0000, v69
	v_pk_mul_f32 v[66:67], v[110:111], v[34:35] op_sel_hi:[0,1]
	v_pk_mul_f32 v[68:69], v[110:111], v[36:37] op_sel_hi:[0,1]
	v_pk_mul_f32 v[70:71], v[110:111], v[38:39] op_sel_hi:[0,1]
	v_pk_mul_f32 v[104:105], v[110:111], v[40:41] op_sel_hi:[0,1]
	global_load_dwordx4 v[38:41], v[96:97], off offset:256 nt
	global_load_dwordx4 v[34:37], v[92:93], off offset:256
	v_pk_mul_f32 v[66:67], v[66:67], v[170:171]
	v_pk_mul_f32 v[68:69], v[68:69], v[174:175]
	v_pk_mul_f32 v[74:75], v[70:71], v[172:173]
	v_pk_mul_f32 v[76:77], v[104:105], v[176:177]
	v_pk_fma_f32 v[66:67], v[84:85], v[66:67], v[98:99]
	v_pk_fma_f32 v[70:71], v[86:87], v[68:69], v[100:101]
	v_pk_fma_f32 v[68:69], v[88:89], v[74:75], v[102:103]
	v_pk_fma_f32 v[72:73], v[90:91], v[76:77], v[72:73]
	global_store_dwordx4 v[94:95], v[66:69], off offset:512
	global_store_dwordx4 v[94:95], v[70:73], off offset:528
	s_nop 0
	v_mul_f32_e32 v86, 0xbfb8aa3b, v113
	v_mul_f32_e32 v30, v30, v86
	v_mul_f32_e32 v26, v26, v86
	v_mul_f32_e32 v31, v31, v86
	v_mul_f32_e32 v27, v27, v86
	v_mul_f32_e32 v32, v32, v86
	v_mul_f32_e32 v33, v33, v86
	v_mul_f32_e32 v28, v28, v86
	v_mul_f32_e32 v29, v29, v86
	v_exp_f32_e32 v30, v30
	v_exp_f32_e32 v26, v26
	v_exp_f32_e32 v31, v31
	v_exp_f32_e32 v27, v27
	v_exp_f32_e32 v32, v32
	v_exp_f32_e32 v33, v33
	v_exp_f32_e32 v28, v28
	v_exp_f32_e32 v29, v29
	v_add_f32_e32 v30, 1.0, v30
	v_add_f32_e32 v76, 1.0, v26
	v_add_f32_e32 v31, 1.0, v31
	v_add_f32_e32 v77, 1.0, v27
	v_add_f32_e32 v32, 1.0, v32
	v_add_f32_e32 v33, 1.0, v33
	v_add_f32_e32 v78, 1.0, v28
	v_add_f32_e32 v79, 1.0, v29
	v_rcp_f32_e32 v26, v30
	v_rcp_f32_e32 v28, v76
	v_rcp_f32_e32 v27, v31
	v_rcp_f32_e32 v29, v77
	v_rcp_f32_e32 v32, v32
	v_rcp_f32_e32 v33, v33
	v_rcp_f32_e32 v76, v78
	v_rcp_f32_e32 v77, v79
	s_waitcnt vmcnt(15)
	v_lshlrev_b32_e32 v30, 16, v62
	v_and_b32_e32 v31, 0xffff0000, v62
	v_lshlrev_b32_e32 v80, 16, v64
	v_and_b32_e32 v81, 0xffff0000, v64
	v_lshlrev_b32_e32 v62, 16, v63
	v_and_b32_e32 v63, 0xffff0000, v63
	v_lshlrev_b64 v[74:75], 12, v[116:117]
	v_lshlrev_b32_e32 v64, 16, v65
	v_and_b32_e32 v65, 0xffff0000, v65
	v_pk_mul_f32 v[30:31], v[112:113], v[30:31] op_sel_hi:[0,1]
	v_pk_mul_f32 v[80:81], v[112:113], v[80:81] op_sel_hi:[0,1]
	v_pk_mul_f32 v[62:63], v[112:113], v[62:63] op_sel_hi:[0,1]
	v_lshl_add_u64 v[74:75], s[48:49], 0, v[74:75]
	s_waitcnt vmcnt(14)
	v_lshlrev_b32_e32 v78, 16, v58
	v_and_b32_e32 v79, 0xffff0000, v58
	v_lshlrev_b32_e32 v84, 16, v60
	v_and_b32_e32 v85, 0xffff0000, v60
	v_lshlrev_b32_e32 v58, 16, v59
	v_and_b32_e32 v59, 0xffff0000, v59
	v_pk_mul_f32 v[64:65], v[112:113], v[64:65] op_sel_hi:[0,1]
	v_lshl_add_u64 v[74:75], v[74:75], 0, v[180:181]
	v_lshlrev_b32_e32 v60, 16, v61
	v_and_b32_e32 v61, 0xffff0000, v61
	v_mul_f32_e32 v22, v22, v86
	v_mul_f32_e32 v18, v18, v86
	v_mul_f32_e32 v23, v23, v86
	v_mul_f32_e32 v19, v19, v86
	v_mul_f32_e32 v24, v24, v86
	v_mul_f32_e32 v25, v25, v86
	v_mul_f32_e32 v20, v20, v86
	v_mul_f32_e32 v21, v21, v86
	v_exp_f32_e32 v22, v22
	v_exp_f32_e32 v18, v18
	v_exp_f32_e32 v23, v23
	v_exp_f32_e32 v19, v19
	v_exp_f32_e32 v24, v24
	v_exp_f32_e32 v25, v25
	v_exp_f32_e32 v20, v20
	v_exp_f32_e32 v21, v21
	v_add_f32_e32 v22, 1.0, v22
	v_add_f32_e32 v23, 1.0, v23
	v_add_f32_e32 v24, 1.0, v24
	v_add_f32_e32 v25, 1.0, v25
	v_rcp_f32_e32 v24, v24
	v_rcp_f32_e32 v25, v25
	v_pk_mul_f32 v[30:31], v[30:31], v[162:163]
	v_pk_mul_f32 v[66:67], v[80:81], v[166:167]
	v_pk_mul_f32 v[62:63], v[62:63], v[164:165]
	v_pk_mul_f32 v[64:65], v[64:65], v[168:169]
	v_pk_fma_f32 v[26:27], v[30:31], v[26:27], v[78:79]
	v_pk_fma_f32 v[30:31], v[66:67], v[28:29], v[84:85]
	v_pk_fma_f32 v[28:29], v[62:63], v[32:33], v[58:59]
	v_pk_fma_f32 v[32:33], v[64:65], v[76:77], v[60:61]
	global_store_dwordx4 v[74:75], v[26:29], off
	global_store_dwordx4 v[74:75], v[30:33], off offset:16
	s_nop 0
	v_add_f32_e32 v58, 1.0, v18
	v_add_f32_e32 v59, 1.0, v19
	v_add_f32_e32 v60, 1.0, v20
	v_add_f32_e32 v61, 1.0, v21
	v_rcp_f32_e32 v18, v22
	v_rcp_f32_e32 v20, v58
	v_rcp_f32_e32 v19, v23
	v_rcp_f32_e32 v21, v59
	v_rcp_f32_e32 v58, v60
	v_rcp_f32_e32 v59, v61
	s_waitcnt vmcnt(13)
	v_lshlrev_b32_e32 v22, 16, v54
	v_and_b32_e32 v23, 0xffff0000, v54
	v_lshlrev_b32_e32 v62, 16, v56
	v_and_b32_e32 v63, 0xffff0000, v56
	v_lshlrev_b32_e32 v54, 16, v55
	v_and_b32_e32 v55, 0xffff0000, v55
	v_lshlrev_b32_e32 v56, 16, v57
	v_and_b32_e32 v57, 0xffff0000, v57
	v_pk_mul_f32 v[22:23], v[112:113], v[22:23] op_sel_hi:[0,1]
	v_pk_mul_f32 v[62:63], v[112:113], v[62:63] op_sel_hi:[0,1]
	v_pk_mul_f32 v[54:55], v[112:113], v[54:55] op_sel_hi:[0,1]
	s_waitcnt vmcnt(12)
	v_lshlrev_b32_e32 v60, 16, v50
	v_and_b32_e32 v61, 0xffff0000, v50
	v_lshlrev_b32_e32 v64, 16, v52
	v_and_b32_e32 v65, 0xffff0000, v52
	v_lshlrev_b32_e32 v50, 16, v51
	v_and_b32_e32 v51, 0xffff0000, v51
	v_pk_mul_f32 v[56:57], v[112:113], v[56:57] op_sel_hi:[0,1]
	v_lshlrev_b32_e32 v52, 16, v53
	v_and_b32_e32 v53, 0xffff0000, v53
	v_pk_mul_f32 v[22:23], v[22:23], v[170:171]
	v_pk_mul_f32 v[26:27], v[62:63], v[174:175]
	v_pk_mul_f32 v[28:29], v[54:55], v[172:173]
	v_pk_mul_f32 v[30:31], v[56:57], v[176:177]
	v_pk_fma_f32 v[18:19], v[18:19], v[22:23], v[60:61]
	v_pk_fma_f32 v[22:23], v[20:21], v[26:27], v[64:65]
	v_pk_fma_f32 v[20:21], v[24:25], v[28:29], v[50:51]
	v_pk_fma_f32 v[24:25], v[58:59], v[30:31], v[52:53]
	global_store_dwordx4 v[74:75], v[18:21], off offset:512
	global_store_dwordx4 v[74:75], v[22:25], off offset:528
	s_nop 0
	v_mul_f32_e32 v52, 0xbfb8aa3b, v111
	v_mul_f32_e32 v14, v14, v52
	v_mul_f32_e32 v10, v10, v52
	v_mul_f32_e32 v15, v15, v52
	v_mul_f32_e32 v11, v11, v52
	v_mul_f32_e32 v16, v16, v52
	v_mul_f32_e32 v17, v17, v52
	v_mul_f32_e32 v12, v12, v52
	v_mul_f32_e32 v13, v13, v52
	v_exp_f32_e32 v14, v14
	v_exp_f32_e32 v10, v10
	v_exp_f32_e32 v15, v15
	v_exp_f32_e32 v11, v11
	v_exp_f32_e32 v16, v16
	v_exp_f32_e32 v17, v17
	v_exp_f32_e32 v12, v12
	v_exp_f32_e32 v13, v13
	v_add_f32_e32 v14, 1.0, v14
	v_add_f32_e32 v28, 1.0, v10
	v_add_f32_e32 v15, 1.0, v15
	v_add_f32_e32 v29, 1.0, v11
	v_add_f32_e32 v16, 1.0, v16
	v_add_f32_e32 v17, 1.0, v17
	v_add_f32_e32 v30, 1.0, v12
	v_add_f32_e32 v31, 1.0, v13
	v_rcp_f32_e32 v10, v14
	v_rcp_f32_e32 v12, v28
	v_rcp_f32_e32 v11, v15
	v_rcp_f32_e32 v13, v29
	v_rcp_f32_e32 v16, v16
	v_rcp_f32_e32 v17, v17
	v_rcp_f32_e32 v28, v30
	v_rcp_f32_e32 v29, v31
	s_waitcnt vmcnt(11)
	v_lshlrev_b32_e32 v14, 16, v46
	v_and_b32_e32 v15, 0xffff0000, v46
	v_lshlrev_b32_e32 v32, 16, v48
	v_and_b32_e32 v33, 0xffff0000, v48
	v_lshlrev_b32_e32 v46, 16, v47
	v_and_b32_e32 v47, 0xffff0000, v47
	v_lshlrev_b64 v[26:27], 12, v[82:83]
	v_lshlrev_b32_e32 v48, 16, v49
	v_and_b32_e32 v49, 0xffff0000, v49
	s_waitcnt lgkmcnt(0)
	v_pk_mul_f32 v[14:15], v[108:109], v[14:15] op_sel_hi:[0,1]
	v_pk_mul_f32 v[32:33], v[108:109], v[32:33] op_sel_hi:[0,1]
	v_pk_mul_f32 v[46:47], v[108:109], v[46:47] op_sel_hi:[0,1]
	v_lshl_add_u64 v[26:27], s[48:49], 0, v[26:27]
	s_waitcnt vmcnt(10)
	v_lshlrev_b32_e32 v30, 16, v42
	v_and_b32_e32 v31, 0xffff0000, v42
	v_lshlrev_b32_e32 v50, 16, v44
	v_and_b32_e32 v51, 0xffff0000, v44
	v_lshlrev_b32_e32 v42, 16, v43
	v_and_b32_e32 v43, 0xffff0000, v43
	v_pk_mul_f32 v[48:49], v[108:109], v[48:49] op_sel_hi:[0,1]
	v_lshl_add_u64 v[26:27], v[26:27], 0, v[180:181]
	v_lshlrev_b32_e32 v44, 16, v45
	v_and_b32_e32 v45, 0xffff0000, v45
	v_mul_f32_e32 v6, v6, v52
	v_mul_f32_e32 v2, v2, v52
	v_mul_f32_e32 v7, v7, v52
	v_mul_f32_e32 v3, v3, v52
	v_mul_f32_e32 v8, v8, v52
	v_mul_f32_e32 v9, v9, v52
	v_mul_f32_e32 v4, v4, v52
	v_mul_f32_e32 v5, v5, v52
	v_exp_f32_e32 v6, v6
	v_exp_f32_e32 v2, v2
	v_exp_f32_e32 v7, v7
	v_exp_f32_e32 v3, v3
	v_exp_f32_e32 v8, v8
	v_exp_f32_e32 v9, v9
	v_exp_f32_e32 v4, v4
	v_exp_f32_e32 v5, v5
	v_add_f32_e32 v6, 1.0, v6
	v_add_f32_e32 v7, 1.0, v7
	v_add_f32_e32 v8, 1.0, v8
	v_add_f32_e32 v9, 1.0, v9
	v_rcp_f32_e32 v8, v8
	v_rcp_f32_e32 v9, v9
	v_pk_mul_f32 v[14:15], v[14:15], v[162:163]
	v_pk_mul_f32 v[18:19], v[32:33], v[166:167]
	v_pk_mul_f32 v[20:21], v[46:47], v[164:165]
	v_pk_mul_f32 v[22:23], v[48:49], v[168:169]
	v_pk_fma_f32 v[10:11], v[14:15], v[10:11], v[30:31]
	v_pk_fma_f32 v[14:15], v[18:19], v[12:13], v[50:51]
	v_pk_fma_f32 v[12:13], v[20:21], v[16:17], v[42:43]
	v_pk_fma_f32 v[16:17], v[22:23], v[28:29], v[44:45]
	global_store_dwordx4 v[26:27], v[10:13], off
	global_store_dwordx4 v[26:27], v[14:17], off offset:16
	s_nop 0
	v_add_f32_e32 v18, 1.0, v2
	v_add_f32_e32 v19, 1.0, v3
	v_add_f32_e32 v20, 1.0, v4
	v_add_f32_e32 v21, 1.0, v5
	v_rcp_f32_e32 v2, v6
	v_rcp_f32_e32 v4, v18
	v_rcp_f32_e32 v3, v7
	v_rcp_f32_e32 v5, v19
	v_rcp_f32_e32 v18, v20
	v_rcp_f32_e32 v19, v21
	s_waitcnt vmcnt(9)
	v_lshlrev_b32_e32 v6, 16, v38
	v_and_b32_e32 v7, 0xffff0000, v38
	v_lshlrev_b32_e32 v22, 16, v40
	v_and_b32_e32 v23, 0xffff0000, v40
	v_lshlrev_b32_e32 v28, 16, v39
	v_and_b32_e32 v29, 0xffff0000, v39
	v_lshlrev_b32_e32 v32, 16, v41
	v_and_b32_e32 v33, 0xffff0000, v41
	v_pk_mul_f32 v[6:7], v[108:109], v[6:7] op_sel_hi:[0,1]
	v_pk_mul_f32 v[22:23], v[108:109], v[22:23] op_sel_hi:[0,1]
	v_pk_mul_f32 v[28:29], v[108:109], v[28:29] op_sel_hi:[0,1]
	s_waitcnt vmcnt(8)
	v_lshlrev_b32_e32 v20, 16, v34
	v_and_b32_e32 v21, 0xffff0000, v34
	v_lshlrev_b32_e32 v24, 16, v36
	v_and_b32_e32 v25, 0xffff0000, v36
	v_lshlrev_b32_e32 v30, 16, v35
	v_and_b32_e32 v31, 0xffff0000, v35
	v_pk_mul_f32 v[32:33], v[108:109], v[32:33] op_sel_hi:[0,1]
	v_lshlrev_b32_e32 v34, 16, v37
	v_and_b32_e32 v35, 0xffff0000, v37
	v_pk_mul_f32 v[6:7], v[6:7], v[170:171]
	v_pk_mul_f32 v[10:11], v[22:23], v[174:175]
	v_pk_mul_f32 v[12:13], v[28:29], v[172:173]
	v_pk_mul_f32 v[14:15], v[32:33], v[176:177]
	v_pk_fma_f32 v[2:3], v[2:3], v[6:7], v[20:21]
	v_pk_fma_f32 v[6:7], v[4:5], v[10:11], v[24:25]
	v_pk_fma_f32 v[4:5], v[8:9], v[12:13], v[30:31]
	v_pk_fma_f32 v[8:9], v[18:19], v[14:15], v[34:35]
	global_store_dwordx4 v[26:27], v[2:5], off offset:512
	global_store_dwordx4 v[26:27], v[6:9], off offset:528
	s_cbranch_vccz .LBB0_755
	s_mov_b64 s[100:101], exec
	v_readlane_b32 s98, v251, 41
	v_readlane_b32 s99, v251, 42
	s_and_b64 s[98:99], s[100:101], s[98:99]
	s_mov_b64 exec, s[98:99]
	s_cbranch_execz .Lmy_pf6_skip
	v_readlane_b32 s98, v251, 20
	v_readlane_b32 s99, v251, 21
	s_add_u32 s98, s98, 0x28200
	s_addc_u32 s99, s99, 0
	v_mov_b32_e32 v252, 0
	global_load_dword v253, v252, s[98:99] sc1
.Lmy_pf6_skip:
	s_mov_b64 exec, s[100:101]
	s_waitcnt vmcnt(0)
	s_cmpk_gt_u32 s36, 0xff
	s_cbranch_scc1 .LBB0_766
	s_barrier

.LBB0_767:
	s_sub_i32 s8, s70, 64
	s_cmpk_gt_u32 s8, 0x7f
	s_barrier
	s_cbranch_scc1 .LBB0_783
	s_and_saveexec_b64 s[0:1], s[2:3]
	s_cbranch_execz .LBB0_780
	v_readfirstlane_b32 s98, v253
	s_cmpk_gt_u32 s98, 0x7f
	s_cbranch_scc1 .LBB0_779
	s_memrealtime s[2:3]
	v_mov_b32_e32 v1, 0
	v_mov_b64_e32 v[2:3], 0x1e8481
	s_branch .LBB0_772
